# instruction selection in the RG-LRU chunk loop: in-row scan with DPP folded into v_fmac/v_mul (identity lanes keep their value) instead of v_mov_dpp copies + packed ops
# baseline (speedup 1.0000x reference)
.LBB0_439:
	s_or_b64 exec, exec, s[50:51]
	s_waitcnt lgkmcnt(0)
	s_barrier
	ds_read_b128 v[56:59], v176 offset:11808
	ds_read_b128 v[52:55], v176 offset:11872
	ds_read_b128 v[48:51], v176 offset:11936
	ds_read_b128 v[24:27], v188 offset:39536
	ds_read_b128 v[28:31], v188 offset:49520
	s_waitcnt lgkmcnt(1)
	v_mfma_f32_16x16x32_bf16 v[24:27], v[24:27], v[56:59], 0
	ds_read_b128 v[32:35], v188 offset:39600
	ds_read_b128 v[36:39], v188 offset:49584
	s_waitcnt lgkmcnt(2)
	v_mfma_f32_16x16x32_bf16 v[28:31], v[28:31], v[56:59], 0
	s_waitcnt lgkmcnt(1)
	v_mfma_f32_16x16x32_bf16 v[24:27], v[32:35], v[52:55], v[24:27]
	ds_read_b128 v[32:35], v188 offset:39664
	ds_read_b128 v[40:43], v188 offset:49648
	s_waitcnt lgkmcnt(2)
	v_mfma_f32_16x16x32_bf16 v[28:31], v[36:39], v[52:55], v[28:31]
	s_waitcnt lgkmcnt(1)
	v_mfma_f32_16x16x32_bf16 v[36:39], v[32:35], v[48:51], v[24:27]
	s_waitcnt lgkmcnt(0)
	v_mfma_f32_16x16x32_bf16 v[24:27], v[40:43], v[48:51], v[28:31]
	ds_read_b128 v[40:43], v150 offset:37408
	s_nop 2
	ds_read_b128 v[28:31], v150 offset:37600
	ds_read_b128 v[44:47], v150 offset:37792
	ds_read_b128 v[32:35], v189 offset:25120
	ds_read_b128 v[220:223], v188 offset:42864
	ds_read_b128 v[224:227], v188 offset:52848
	ds_read_b128 v[228:231], v188 offset:42928
	ds_read_b128 v[232:235], v188 offset:52912
	s_waitcnt lgkmcnt(7)
	v_add_f32_e32 v236, v36, v40
	v_add_f32_e32 v237, v37, v41
	v_add_f32_e32 v238, v38, v42
	v_add_f32_e32 v239, v39, v43
	v_mul_f32_e32 v236, 0xbfb8aa3b, v236
	v_mul_f32_e32 v237, 0xbfb8aa3b, v237
	v_mul_f32_e32 v238, 0xbfb8aa3b, v238
	v_mul_f32_e32 v239, 0xbfb8aa3b, v239
	v_exp_f32_e32 v236, v236
	v_exp_f32_e32 v237, v237
	v_exp_f32_e32 v238, v238
	v_exp_f32_e32 v239, v239
	v_add_f32_e32 v236, 1.0, v236
	v_add_f32_e32 v237, 1.0, v237
	v_add_f32_e32 v238, 1.0, v238
	v_add_f32_e32 v239, 1.0, v239
	v_rcp_f32_e32 v236, v236
	v_rcp_f32_e32 v237, v237
	v_rcp_f32_e32 v238, v238
	v_rcp_f32_e32 v239, v239
	s_waitcnt lgkmcnt(5)
	v_mul_f32_e32 v240, v44, v236
	v_mul_f32_e32 v241, v45, v237
	v_mul_f32_e32 v242, v46, v238
	v_mul_f32_e32 v243, v47, v239
	v_mul_f32_e32 v236, 0x3fb8aa3b, v240
	v_mul_f32_e32 v237, 0x3fb8aa3b, v241
	v_mul_f32_e32 v238, 0x3fb8aa3b, v242
	v_mul_f32_e32 v239, 0x3fb8aa3b, v243
	v_exp_f32_e32 v0, v236
	v_exp_f32_e32 v3, v237
	v_exp_f32_e32 v209, v238
	v_exp_f32_e32 v213, v239
	v_add_f32_e32 v240, v240, v240
	v_add_f32_e32 v241, v241, v241
	v_add_f32_e32 v242, v242, v242
	v_add_f32_e32 v243, v243, v243
	v_fmamk_f32 v236, v240, 0x3d2aaaab, v177
	v_fmamk_f32 v237, v241, 0x3d2aaaab, v177
	v_fmamk_f32 v238, v242, 0x3d2aaaab, v177
	v_fmamk_f32 v239, v243, 0x3d2aaaab, v177
	v_fma_f32 v236, v240, v236, 0.5
	v_fma_f32 v237, v241, v237, 0.5
	v_fma_f32 v238, v242, v238, 0.5
	v_fma_f32 v239, v243, v239, 0.5
	v_fma_f32 v236, v240, v236, 1.0
	v_fma_f32 v237, v241, v237, 1.0
	v_fma_f32 v238, v242, v238, 1.0
	v_fma_f32 v239, v243, v239, 1.0
	v_mul_f32_e64 v236, v236, -v240
	v_mul_f32_e64 v237, v237, -v241
	v_mul_f32_e64 v238, v238, -v242
	v_mul_f32_e64 v239, v239, -v243
	v_cmp_nlt_f32_e64 s[0:1], s79, v240
	v_cmp_nlt_f32_e64 s[50:51], s79, v241
	v_fma_f32 v244, -v0, v0, 1.0
	v_fma_f32 v245, -v3, v3, 1.0
	v_cndmask_b32_e64 v2, v236, v244, s[0:1]
	v_cndmask_b32_e64 v206, v237, v245, s[50:51]
	v_cmp_nlt_f32_e64 s[0:1], s79, v242
	v_cmp_nlt_f32_e64 s[50:51], s79, v243
	v_fma_f32 v246, -v209, v209, 1.0
	v_fma_f32 v247, -v213, v213, 1.0
	v_cndmask_b32_e64 v210, v238, v246, s[0:1]
	v_cndmask_b32_e64 v214, v239, v247, s[50:51]
	s_waitcnt lgkmcnt(3)
	v_mfma_f32_16x16x32_bf16 v[36:39], v[220:223], v[56:59], 0
	s_waitcnt lgkmcnt(2)
	v_mfma_f32_16x16x32_bf16 v[40:43], v[224:227], v[56:59], 0
	s_waitcnt lgkmcnt(1)
	v_mfma_f32_16x16x32_bf16 v[36:39], v[228:231], v[52:55], v[36:39]
	ds_read_b128 v[44:47], v188 offset:42992
	ds_read_b128 v[64:67], v188 offset:52976
	s_waitcnt lgkmcnt(2)
	v_mfma_f32_16x16x32_bf16 v[40:43], v[232:235], v[52:55], v[40:43]
	s_waitcnt lgkmcnt(1)
	v_mfma_f32_16x16x32_bf16 v[60:63], v[44:47], v[48:51], v[36:39]
	s_waitcnt lgkmcnt(0)
	v_mfma_f32_16x16x32_bf16 v[36:39], v[64:67], v[48:51], v[40:43]
	ds_read_b128 v[64:67], v150 offset:37472
	s_nop 2
	ds_read_b128 v[40:43], v150 offset:37664
	ds_read_b128 v[68:71], v150 offset:37856
	ds_read_b128 v[44:47], v189 offset:25184
	ds_read_b128 v[220:223], v188 offset:46192
	ds_read_b128 v[224:227], v188 offset:56176
	ds_read_b128 v[228:231], v188 offset:46256
	ds_read_b128 v[232:235], v188 offset:56240
	s_waitcnt lgkmcnt(7)
	v_add_f32_e32 v236, v60, v64
	v_add_f32_e32 v237, v61, v65
	v_add_f32_e32 v238, v62, v66
	v_add_f32_e32 v239, v63, v67
	v_mul_f32_e32 v236, 0xbfb8aa3b, v236
	v_mul_f32_e32 v237, 0xbfb8aa3b, v237
	v_mul_f32_e32 v238, 0xbfb8aa3b, v238
	v_mul_f32_e32 v239, 0xbfb8aa3b, v239
	v_exp_f32_e32 v236, v236
	v_exp_f32_e32 v237, v237
	v_exp_f32_e32 v238, v238
	v_exp_f32_e32 v239, v239
	v_add_f32_e32 v236, 1.0, v236
	v_add_f32_e32 v237, 1.0, v237
	v_add_f32_e32 v238, 1.0, v238
	v_add_f32_e32 v239, 1.0, v239
	v_rcp_f32_e32 v236, v236
	v_rcp_f32_e32 v237, v237
	v_rcp_f32_e32 v238, v238
	v_rcp_f32_e32 v239, v239
	s_waitcnt lgkmcnt(5)
	v_mul_f32_e32 v240, v68, v236
	v_mul_f32_e32 v241, v69, v237
	v_mul_f32_e32 v242, v70, v238
	v_mul_f32_e32 v243, v71, v239
	v_mul_f32_e32 v236, 0x3fb8aa3b, v240
	v_mul_f32_e32 v237, 0x3fb8aa3b, v241
	v_mul_f32_e32 v238, 0x3fb8aa3b, v242
	v_mul_f32_e32 v239, 0x3fb8aa3b, v243
	v_exp_f32_e32 v207, v236
	v_exp_f32_e32 v211, v237
	v_exp_f32_e32 v215, v238
	v_exp_f32_e32 v217, v239
	v_add_f32_e32 v240, v240, v240
	v_add_f32_e32 v241, v241, v241
	v_add_f32_e32 v242, v242, v242
	v_add_f32_e32 v243, v243, v243
	v_fmamk_f32 v236, v240, 0x3d2aaaab, v177
	v_fmamk_f32 v237, v241, 0x3d2aaaab, v177
	v_fmamk_f32 v238, v242, 0x3d2aaaab, v177
	v_fmamk_f32 v239, v243, 0x3d2aaaab, v177
	v_fma_f32 v236, v240, v236, 0.5
	v_fma_f32 v237, v241, v237, 0.5
	v_fma_f32 v238, v242, v238, 0.5
	v_fma_f32 v239, v243, v239, 0.5
	v_fma_f32 v236, v240, v236, 1.0
	v_fma_f32 v237, v241, v237, 1.0
	v_fma_f32 v238, v242, v238, 1.0
	v_fma_f32 v239, v243, v239, 1.0
	v_mul_f32_e64 v236, v236, -v240
	v_mul_f32_e64 v237, v237, -v241
	v_mul_f32_e64 v238, v238, -v242
	v_mul_f32_e64 v239, v239, -v243
	v_cmp_nlt_f32_e64 s[0:1], s79, v240
	v_cmp_nlt_f32_e64 s[50:51], s79, v241
	v_fma_f32 v244, -v207, v207, 1.0
	v_fma_f32 v245, -v211, v211, 1.0
	v_cndmask_b32_e64 v208, v236, v244, s[0:1]
	v_cndmask_b32_e64 v212, v237, v245, s[50:51]
	v_cmp_nlt_f32_e64 s[0:1], s79, v242
	v_cmp_nlt_f32_e64 s[50:51], s79, v243
	v_fma_f32 v246, -v215, v215, 1.0
	v_fma_f32 v247, -v217, v217, 1.0
	v_cndmask_b32_e64 v216, v238, v246, s[0:1]
	v_cndmask_b32_e64 v218, v239, v247, s[50:51]
	s_waitcnt lgkmcnt(3)
	v_mfma_f32_16x16x32_bf16 v[60:63], v[220:223], v[56:59], 0
	s_waitcnt lgkmcnt(2)
	v_mfma_f32_16x16x32_bf16 v[56:59], v[224:227], v[56:59], 0
	s_waitcnt lgkmcnt(1)
	v_mfma_f32_16x16x32_bf16 v[60:63], v[228:231], v[52:55], v[60:63]
	s_waitcnt lgkmcnt(0)
	s_nop 1
	v_mfma_f32_16x16x32_bf16 v[52:55], v[232:235], v[52:55], v[56:59]
	s_nop 2
	ds_read_b128 v[56:59], v188 offset:46320
	ds_read_b128 v[64:67], v188 offset:56304
	s_waitcnt lgkmcnt(1)
	v_mfma_f32_16x16x32_bf16 v[60:63], v[56:59], v[48:51], v[60:63]
	s_waitcnt lgkmcnt(0)
	v_mfma_f32_16x16x32_bf16 v[48:51], v[64:67], v[48:51], v[52:55]
	ds_read_b128 v[64:67], v150 offset:37536
	s_nop 1
	ds_read_b128 v[52:55], v150 offset:37728
	ds_read_b128 v[68:71], v150 offset:37920
	ds_read_b128 v[56:59], v189 offset:25248
	s_waitcnt lgkmcnt(3)
	v_add_f32_e32 v236, v60, v64
	v_add_f32_e32 v237, v61, v65
	v_add_f32_e32 v238, v62, v66
	v_add_f32_e32 v239, v63, v67
	v_mul_f32_e32 v236, 0xbfb8aa3b, v236
	v_mul_f32_e32 v237, 0xbfb8aa3b, v237
	v_mul_f32_e32 v238, 0xbfb8aa3b, v238
	v_mul_f32_e32 v239, 0xbfb8aa3b, v239
	v_exp_f32_e32 v236, v236
	v_exp_f32_e32 v237, v237
	v_exp_f32_e32 v238, v238
	v_exp_f32_e32 v239, v239
	v_add_f32_e32 v236, 1.0, v236
	v_add_f32_e32 v237, 1.0, v237
	v_add_f32_e32 v238, 1.0, v238
	v_add_f32_e32 v239, 1.0, v239
	v_rcp_f32_e32 v236, v236
	v_rcp_f32_e32 v237, v237
	v_rcp_f32_e32 v238, v238
	v_rcp_f32_e32 v239, v239
	s_waitcnt lgkmcnt(1)
	v_mul_f32_e32 v240, v68, v236
	v_mul_f32_e32 v241, v69, v237
	v_mul_f32_e32 v242, v70, v238
	v_mul_f32_e32 v243, v71, v239
	v_mul_f32_e32 v236, 0x3fb8aa3b, v240
	v_mul_f32_e32 v237, 0x3fb8aa3b, v241
	v_mul_f32_e32 v238, 0x3fb8aa3b, v242
	v_mul_f32_e32 v239, 0x3fb8aa3b, v243
	v_exp_f32_e32 v60, v236
	v_exp_f32_e32 v61, v237
	v_exp_f32_e32 v62, v238
	v_exp_f32_e32 v63, v239
	v_add_f32_e32 v240, v240, v240
	v_add_f32_e32 v241, v241, v241
	v_add_f32_e32 v242, v242, v242
	v_add_f32_e32 v243, v243, v243
	v_fmamk_f32 v236, v240, 0x3d2aaaab, v177
	v_fmamk_f32 v237, v241, 0x3d2aaaab, v177
	v_fmamk_f32 v238, v242, 0x3d2aaaab, v177
	v_fmamk_f32 v239, v243, 0x3d2aaaab, v177
	v_fma_f32 v236, v240, v236, 0.5
	v_fma_f32 v237, v241, v237, 0.5
	v_fma_f32 v238, v242, v238, 0.5
	v_fma_f32 v239, v243, v239, 0.5
	v_fma_f32 v236, v240, v236, 1.0
	v_fma_f32 v237, v241, v237, 1.0
	v_fma_f32 v238, v242, v238, 1.0
	v_fma_f32 v239, v243, v239, 1.0
	v_mul_f32_e64 v236, v236, -v240
	v_mul_f32_e64 v237, v237, -v241
	v_mul_f32_e64 v238, v238, -v242
	v_mul_f32_e64 v239, v239, -v243
	v_cmp_nlt_f32_e64 s[0:1], s79, v240
	v_cmp_nlt_f32_e64 s[50:51], s79, v241
	v_fma_f32 v244, -v60, v60, 1.0
	v_fma_f32 v245, -v61, v61, 1.0
	v_cndmask_b32_e64 v64, v236, v244, s[0:1]
	v_cndmask_b32_e64 v65, v237, v245, s[50:51]
	v_cmp_nlt_f32_e64 s[0:1], s79, v242
	v_cmp_nlt_f32_e64 s[50:51], s79, v243
	v_fma_f32 v246, -v62, v62, 1.0
	v_fma_f32 v247, -v63, v63, 1.0
	v_cndmask_b32_e64 v66, v238, v246, s[0:1]
	v_cndmask_b32_e64 v67, v239, v247, s[50:51]
	v_add_f32_e32 v27, v27, v31
	v_mul_f32_e32 v27, 0xbfb8aa3b, v27
	v_exp_f32_e32 v31, v27
	v_sqrt_f32_e32 v69, v214
	v_or_b32_e32 v68, s33, v142
	v_add_f32_e32 v26, v26, v30
	v_add_f32_e32 v31, 1.0, v31
	v_rcp_f32_e32 v31, v31
	v_cmp_ne_u32_e64 s[0:1], 0, v68
	v_mul_f32_e32 v26, 0xbfb8aa3b, v26
	s_or_b64 s[50:51], s[30:31], s[0:1]
	v_exp_f32_e32 v26, v26
	v_cndmask_b32_e64 v68, 1.0, v69, s[50:51]
	v_mul_f32_e32 v31, v31, v68
	v_mul_f32_e32 v30, v35, v31
	v_cndmask_b32_e64 v31, v30, 0, s[46:47]
	v_sqrt_f32_e32 v30, v210
	v_add_f32_e32 v26, 1.0, v26
	v_rcp_f32_e32 v35, v26
	v_add_f32_e32 v25, v25, v29
	v_mul_f32_e32 v25, 0xbfb8aa3b, v25
	v_exp_f32_e32 v25, v25
	v_cndmask_b32_e64 v30, 1.0, v30, s[50:51]
	v_mul_f32_e32 v29, v35, v30
	v_mul_f32_e32 v29, v34, v29
	v_add_f32_e32 v24, v24, v28
	v_cndmask_b32_e64 v30, v29, 0, s[46:47]
	v_add_f32_e32 v25, 1.0, v25
	v_sqrt_f32_e32 v29, v206
	v_mul_f32_e32 v24, 0xbfb8aa3b, v24
	v_rcp_f32_e32 v25, v25
	v_exp_f32_e32 v24, v24
	v_cndmask_b32_e64 v28, 1.0, v29, s[50:51]
	v_cndmask_b32_e64 v3, v3, 1.0, s[46:47]
	v_mul_f32_e32 v25, v25, v28
	v_add_f32_e32 v24, 1.0, v24
	v_sqrt_f32_e32 v28, v2
	v_rcp_f32_e32 v24, v24
	v_cndmask_b32_e64 v2, v0, 1.0, s[46:47]
	v_mul_f32_e32 v25, v33, v25
	v_cndmask_b32_e64 v0, 1.0, v28, s[50:51]
	v_mul_f32_e32 v0, v24, v0
	v_mul_f32_e32 v0, v32, v0
	v_cndmask_b32_e64 v25, v25, 0, s[46:47]
	v_cndmask_b32_e64 v24, v0, 0, s[46:47]
	v_mov_b32_e32 v28, v2
	v_mov_b32_e32 v29, v3
	v_mov_b32_e32 v26, v30
	v_mov_b32_e32 v27, v31
	v_cndmask_b32_e64 v31, v213, 1.0, s[46:47]
	v_cndmask_b32_e64 v30, v209, 1.0, s[46:47]
	s_nop 1
	v_fmac_f32_dpp v24, v24, v28 row_shr:1 row_mask:0xf bank_mask:0xf
	v_fmac_f32_dpp v25, v25, v29 row_shr:1 row_mask:0xf bank_mask:0xf
	v_fmac_f32_dpp v26, v26, v30 row_shr:1 row_mask:0xf bank_mask:0xf
	v_fmac_f32_dpp v27, v27, v31 row_shr:1 row_mask:0xf bank_mask:0xf
	v_mul_f32_dpp v28, v28, v28 row_shr:1 row_mask:0xf bank_mask:0xf
	v_mul_f32_dpp v29, v29, v29 row_shr:1 row_mask:0xf bank_mask:0xf
	v_mul_f32_dpp v30, v30, v30 row_shr:1 row_mask:0xf bank_mask:0xf
	v_mul_f32_dpp v31, v31, v31 row_shr:1 row_mask:0xf bank_mask:0xf
	v_fmac_f32_dpp v24, v24, v28 row_shr:2 row_mask:0xf bank_mask:0xf
	v_fmac_f32_dpp v25, v25, v29 row_shr:2 row_mask:0xf bank_mask:0xf
	v_fmac_f32_dpp v26, v26, v30 row_shr:2 row_mask:0xf bank_mask:0xf
	v_fmac_f32_dpp v27, v27, v31 row_shr:2 row_mask:0xf bank_mask:0xf
	v_mul_f32_dpp v28, v28, v28 row_shr:2 row_mask:0xf bank_mask:0xf
	v_mul_f32_dpp v29, v29, v29 row_shr:2 row_mask:0xf bank_mask:0xf
	v_mul_f32_dpp v30, v30, v30 row_shr:2 row_mask:0xf bank_mask:0xf
	v_mul_f32_dpp v31, v31, v31 row_shr:2 row_mask:0xf bank_mask:0xf
	v_fmac_f32_dpp v24, v24, v28 row_shr:4 row_mask:0xf bank_mask:0xf
	v_fmac_f32_dpp v25, v25, v29 row_shr:4 row_mask:0xf bank_mask:0xf
	v_fmac_f32_dpp v26, v26, v30 row_shr:4 row_mask:0xf bank_mask:0xf
	v_fmac_f32_dpp v27, v27, v31 row_shr:4 row_mask:0xf bank_mask:0xf
	v_mul_f32_dpp v28, v28, v28 row_shr:4 row_mask:0xf bank_mask:0xf
	v_mul_f32_dpp v29, v29, v29 row_shr:4 row_mask:0xf bank_mask:0xf
	v_mul_f32_dpp v30, v30, v30 row_shr:4 row_mask:0xf bank_mask:0xf
	v_mul_f32_dpp v31, v31, v31 row_shr:4 row_mask:0xf bank_mask:0xf
	v_fmac_f32_dpp v24, v24, v28 row_shr:8 row_mask:0xf bank_mask:0xf
	v_fmac_f32_dpp v25, v25, v29 row_shr:8 row_mask:0xf bank_mask:0xf
	v_fmac_f32_dpp v26, v26, v30 row_shr:8 row_mask:0xf bank_mask:0xf
	v_fmac_f32_dpp v27, v27, v31 row_shr:8 row_mask:0xf bank_mask:0xf
	v_mul_f32_dpp v28, v28, v28 row_shr:8 row_mask:0xf bank_mask:0xf
	v_mul_f32_dpp v29, v29, v29 row_shr:8 row_mask:0xf bank_mask:0xf
	v_mul_f32_dpp v30, v30, v30 row_shr:8 row_mask:0xf bank_mask:0xf
	v_mul_f32_dpp v31, v31, v31 row_shr:8 row_mask:0xf bank_mask:0xf
	s_and_saveexec_b64 s[0:1], s[18:19]
	s_cbranch_execz .LBB0_489
	ds_write_b128 v153, v[28:31] offset:37984
	ds_write_b128 v153, v[24:27] offset:38752
.LBB0_489:
	s_or_b64 exec, exec, s[0:1]
	v_add_f32_e32 v0, v39, v43
	v_mul_f32_e32 v0, 0xbfb8aa3b, v0
	v_exp_f32_e32 v0, v0
	v_sqrt_f32_e32 v2, v218
	v_add_f32_e32 v32, v38, v42
	v_mul_f32_e32 v32, 0xbfb8aa3b, v32
	v_add_f32_e32 v0, 1.0, v0
	v_rcp_f32_e32 v0, v0
	v_exp_f32_e32 v32, v32
	v_cndmask_b32_e64 v2, 1.0, v2, s[50:51]
	v_add_f32_e32 v33, v37, v41
	v_mul_f32_e32 v0, v0, v2
	v_mul_f32_e32 v0, v47, v0
	v_cndmask_b32_e64 v35, v0, 0, s[46:47]
	v_sqrt_f32_e32 v0, v216
	v_add_f32_e32 v2, 1.0, v32
	v_rcp_f32_e32 v32, v2
	v_mul_f32_e32 v33, 0xbfb8aa3b, v33
	v_exp_f32_e32 v33, v33
	v_cndmask_b32_e64 v0, 1.0, v0, s[50:51]
	v_mul_f32_e32 v0, v32, v0
	v_mul_f32_e32 v0, v46, v0
	v_add_f32_e32 v36, v36, v40
	v_cndmask_b32_e64 v34, v0, 0, s[46:47]
	v_add_f32_e32 v0, 1.0, v33
	v_sqrt_f32_e32 v32, v212
	v_mul_f32_e32 v36, 0xbfb8aa3b, v36
	v_rcp_f32_e32 v0, v0
	v_exp_f32_e32 v36, v36
	v_cndmask_b32_e64 v32, 1.0, v32, s[50:51]
	v_cndmask_b32_e64 v33, v211, 1.0, s[46:47]
	v_mul_f32_e32 v0, v0, v32
	v_add_f32_e32 v32, 1.0, v36
	v_sqrt_f32_e32 v36, v208
	v_rcp_f32_e32 v38, v32
	v_mul_f32_e32 v0, v45, v0
	v_cndmask_b32_e64 v37, v0, 0, s[46:47]
	v_cndmask_b32_e64 v0, 1.0, v36, s[50:51]
	v_mul_f32_e32 v0, v38, v0
	v_mul_f32_e32 v0, v44, v0
	v_cndmask_b32_e64 v32, v207, 1.0, s[46:47]
	v_cndmask_b32_e64 v36, v0, 0, s[46:47]
	v_swap_b32 v32, v36
	v_swap_b32 v33, v37
	v_cndmask_b32_e64 v39, v217, 1.0, s[46:47]
	v_cndmask_b32_e64 v38, v215, 1.0, s[46:47]
	s_nop 1
	v_fmac_f32_dpp v32, v32, v36 row_shr:1 row_mask:0xf bank_mask:0xf
	v_fmac_f32_dpp v33, v33, v37 row_shr:1 row_mask:0xf bank_mask:0xf
	v_fmac_f32_dpp v34, v34, v38 row_shr:1 row_mask:0xf bank_mask:0xf
	v_fmac_f32_dpp v35, v35, v39 row_shr:1 row_mask:0xf bank_mask:0xf
	v_mul_f32_dpp v36, v36, v36 row_shr:1 row_mask:0xf bank_mask:0xf
	v_mul_f32_dpp v37, v37, v37 row_shr:1 row_mask:0xf bank_mask:0xf
	v_mul_f32_dpp v38, v38, v38 row_shr:1 row_mask:0xf bank_mask:0xf
	v_mul_f32_dpp v39, v39, v39 row_shr:1 row_mask:0xf bank_mask:0xf
	v_fmac_f32_dpp v32, v32, v36 row_shr:2 row_mask:0xf bank_mask:0xf
	v_fmac_f32_dpp v33, v33, v37 row_shr:2 row_mask:0xf bank_mask:0xf
	v_fmac_f32_dpp v34, v34, v38 row_shr:2 row_mask:0xf bank_mask:0xf
	v_fmac_f32_dpp v35, v35, v39 row_shr:2 row_mask:0xf bank_mask:0xf
	v_mul_f32_dpp v36, v36, v36 row_shr:2 row_mask:0xf bank_mask:0xf
	v_mul_f32_dpp v37, v37, v37 row_shr:2 row_mask:0xf bank_mask:0xf
	v_mul_f32_dpp v38, v38, v38 row_shr:2 row_mask:0xf bank_mask:0xf
	v_mul_f32_dpp v39, v39, v39 row_shr:2 row_mask:0xf bank_mask:0xf
	v_fmac_f32_dpp v32, v32, v36 row_shr:4 row_mask:0xf bank_mask:0xf
	v_fmac_f32_dpp v33, v33, v37 row_shr:4 row_mask:0xf bank_mask:0xf
	v_fmac_f32_dpp v34, v34, v38 row_shr:4 row_mask:0xf bank_mask:0xf
	v_fmac_f32_dpp v35, v35, v39 row_shr:4 row_mask:0xf bank_mask:0xf
	v_mul_f32_dpp v36, v36, v36 row_shr:4 row_mask:0xf bank_mask:0xf
	v_mul_f32_dpp v37, v37, v37 row_shr:4 row_mask:0xf bank_mask:0xf
	v_mul_f32_dpp v38, v38, v38 row_shr:4 row_mask:0xf bank_mask:0xf
	v_mul_f32_dpp v39, v39, v39 row_shr:4 row_mask:0xf bank_mask:0xf
	v_fmac_f32_dpp v32, v32, v36 row_shr:8 row_mask:0xf bank_mask:0xf
	v_fmac_f32_dpp v33, v33, v37 row_shr:8 row_mask:0xf bank_mask:0xf
	v_fmac_f32_dpp v34, v34, v38 row_shr:8 row_mask:0xf bank_mask:0xf
	v_fmac_f32_dpp v35, v35, v39 row_shr:8 row_mask:0xf bank_mask:0xf
	v_mul_f32_dpp v36, v36, v36 row_shr:8 row_mask:0xf bank_mask:0xf
	v_mul_f32_dpp v37, v37, v37 row_shr:8 row_mask:0xf bank_mask:0xf
	v_mul_f32_dpp v38, v38, v38 row_shr:8 row_mask:0xf bank_mask:0xf
	v_mul_f32_dpp v39, v39, v39 row_shr:8 row_mask:0xf bank_mask:0xf
	s_and_saveexec_b64 s[0:1], s[18:19]
	s_cbranch_execz .LBB0_491
	ds_write_b128 v153, v[36:39] offset:38048
	ds_write_b128 v153, v[32:35] offset:38816
.LBB0_491:
	s_or_b64 exec, exec, s[0:1]
	v_add_f32_e32 v0, v51, v55
	v_mul_f32_e32 v0, 0xbfb8aa3b, v0
	v_exp_f32_e32 v0, v0
	v_sqrt_f32_e32 v2, v67
	v_add_f32_e32 v40, v50, v54
	v_mul_f32_e32 v40, 0xbfb8aa3b, v40
	v_add_f32_e32 v0, 1.0, v0
	v_rcp_f32_e32 v0, v0
	v_exp_f32_e32 v40, v40
	v_cndmask_b32_e64 v2, 1.0, v2, s[50:51]
	v_add_f32_e32 v41, v49, v53
	v_mul_f32_e32 v0, v0, v2
	s_waitcnt lgkmcnt(0)
	v_mul_f32_e32 v0, v59, v0
	v_cndmask_b32_e64 v43, v0, 0, s[46:47]
	v_sqrt_f32_e32 v0, v66
	v_add_f32_e32 v2, 1.0, v40
	v_rcp_f32_e32 v40, v2
	v_mul_f32_e32 v41, 0xbfb8aa3b, v41
	v_exp_f32_e32 v41, v41
	v_cndmask_b32_e64 v0, 1.0, v0, s[50:51]
	v_mul_f32_e32 v0, v40, v0
	v_mul_f32_e32 v0, v58, v0
	v_add_f32_e32 v44, v48, v52
	v_cndmask_b32_e64 v42, v0, 0, s[46:47]
	v_add_f32_e32 v0, 1.0, v41
	v_sqrt_f32_e32 v40, v65
	v_mul_f32_e32 v44, 0xbfb8aa3b, v44
	v_rcp_f32_e32 v0, v0
	v_exp_f32_e32 v44, v44
	v_cndmask_b32_e64 v40, 1.0, v40, s[50:51]
	v_cndmask_b32_e64 v41, v61, 1.0, s[46:47]
	v_mul_f32_e32 v0, v0, v40
	v_add_f32_e32 v40, 1.0, v44
	v_sqrt_f32_e32 v44, v64
	v_rcp_f32_e32 v46, v40
	v_mul_f32_e32 v0, v57, v0
	v_cndmask_b32_e64 v45, v0, 0, s[46:47]
	v_cndmask_b32_e64 v0, 1.0, v44, s[50:51]
	v_mul_f32_e32 v0, v46, v0
	v_mul_f32_e32 v0, v56, v0
	v_cndmask_b32_e64 v40, v60, 1.0, s[46:47]
	v_cndmask_b32_e64 v44, v0, 0, s[46:47]
	v_swap_b32 v40, v44
	v_swap_b32 v41, v45
	v_cndmask_b32_e64 v47, v63, 1.0, s[46:47]
	v_cndmask_b32_e64 v46, v62, 1.0, s[46:47]
	s_nop 1
	v_fmac_f32_dpp v40, v40, v44 row_shr:1 row_mask:0xf bank_mask:0xf
	v_fmac_f32_dpp v41, v41, v45 row_shr:1 row_mask:0xf bank_mask:0xf
	v_fmac_f32_dpp v42, v42, v46 row_shr:1 row_mask:0xf bank_mask:0xf
	v_fmac_f32_dpp v43, v43, v47 row_shr:1 row_mask:0xf bank_mask:0xf
	v_mul_f32_dpp v44, v44, v44 row_shr:1 row_mask:0xf bank_mask:0xf
	v_mul_f32_dpp v45, v45, v45 row_shr:1 row_mask:0xf bank_mask:0xf
	v_mul_f32_dpp v46, v46, v46 row_shr:1 row_mask:0xf bank_mask:0xf
	v_mul_f32_dpp v47, v47, v47 row_shr:1 row_mask:0xf bank_mask:0xf
	v_fmac_f32_dpp v40, v40, v44 row_shr:2 row_mask:0xf bank_mask:0xf
	v_fmac_f32_dpp v41, v41, v45 row_shr:2 row_mask:0xf bank_mask:0xf
	v_fmac_f32_dpp v42, v42, v46 row_shr:2 row_mask:0xf bank_mask:0xf
	v_fmac_f32_dpp v43, v43, v47 row_shr:2 row_mask:0xf bank_mask:0xf
	v_mul_f32_dpp v44, v44, v44 row_shr:2 row_mask:0xf bank_mask:0xf
	v_mul_f32_dpp v45, v45, v45 row_shr:2 row_mask:0xf bank_mask:0xf
	v_mul_f32_dpp v46, v46, v46 row_shr:2 row_mask:0xf bank_mask:0xf
	v_mul_f32_dpp v47, v47, v47 row_shr:2 row_mask:0xf bank_mask:0xf
	v_fmac_f32_dpp v40, v40, v44 row_shr:4 row_mask:0xf bank_mask:0xf
	v_fmac_f32_dpp v41, v41, v45 row_shr:4 row_mask:0xf bank_mask:0xf
	v_fmac_f32_dpp v42, v42, v46 row_shr:4 row_mask:0xf bank_mask:0xf
	v_fmac_f32_dpp v43, v43, v47 row_shr:4 row_mask:0xf bank_mask:0xf
	v_mul_f32_dpp v44, v44, v44 row_shr:4 row_mask:0xf bank_mask:0xf
	v_mul_f32_dpp v45, v45, v45 row_shr:4 row_mask:0xf bank_mask:0xf
	v_mul_f32_dpp v46, v46, v46 row_shr:4 row_mask:0xf bank_mask:0xf
	v_mul_f32_dpp v47, v47, v47 row_shr:4 row_mask:0xf bank_mask:0xf
	v_fmac_f32_dpp v40, v40, v44 row_shr:8 row_mask:0xf bank_mask:0xf
	v_fmac_f32_dpp v41, v41, v45 row_shr:8 row_mask:0xf bank_mask:0xf
	v_fmac_f32_dpp v42, v42, v46 row_shr:8 row_mask:0xf bank_mask:0xf
	v_fmac_f32_dpp v43, v43, v47 row_shr:8 row_mask:0xf bank_mask:0xf
	v_mul_f32_dpp v44, v44, v44 row_shr:8 row_mask:0xf bank_mask:0xf
	v_mul_f32_dpp v45, v45, v45 row_shr:8 row_mask:0xf bank_mask:0xf
	v_mul_f32_dpp v46, v46, v46 row_shr:8 row_mask:0xf bank_mask:0xf
	v_mul_f32_dpp v47, v47, v47 row_shr:8 row_mask:0xf bank_mask:0xf
	s_and_saveexec_b64 s[0:1], s[18:19]
	s_cbranch_execz .LBB0_493
	ds_write_b128 v153, v[44:47] offset:38112
	ds_write_b128 v153, v[40:43] offset:38880
